# v34 + MLA half 2: fmamk straight into exp dst regs, all 32 v_exp spread over QK MFMA gaps behind K-fragment ds_read pairs
# speedup vs baseline: 1.0109x; 1.0109x over previous
.LBB0_549:
	v_cndmask_b32_e64 v165, v165, v202, s[4:5]
	v_mul_f32_e32 v154, 0xbdd53b94, v165
	v_fmamk_f32 v202, v69, 0x3dd53b94, v154
	v_fmamk_f32 v215, v70, 0x3dd53b94, v154
	v_fmamk_f32 v155, v66, 0x3dd53b94, v154
	v_fmamk_f32 v156, v67, 0x3dd53b94, v154
	v_fmamk_f32 v157, v68, 0x3dd53b94, v154
	v_fmamk_f32 v216, v71, 0x3dd53b94, v154
	v_fmamk_f32 v217, v72, 0x3dd53b94, v154
	v_fmamk_f32 v218, v73, 0x3dd53b94, v154
	ds_read_b128 v[66:69], v174 offset:32768
	ds_read_b128 v[70:73], v174 offset:40960
	ds_read_b128 v[146:149], v176 offset:32768
	ds_read_b128 v[150:153], v176 offset:40960
	v_fmamk_f32 v224, v82, 0x3dd53b94, v154
	v_fmamk_f32 v225, v83, 0x3dd53b94, v154
	v_fmamk_f32 v226, v84, 0x3dd53b94, v154
	v_fmamk_f32 v227, v85, 0x3dd53b94, v154
	v_fmamk_f32 v228, v86, 0x3dd53b94, v154
	v_fmamk_f32 v229, v87, 0x3dd53b94, v154
	v_fmamk_f32 v230, v88, 0x3dd53b94, v154
	v_fmamk_f32 v231, v89, 0x3dd53b94, v154
	v_fmamk_f32 v234, v90, 0x3dd53b94, v154
	v_fmamk_f32 v235, v91, 0x3dd53b94, v154
	v_fmamk_f32 v236, v92, 0x3dd53b94, v154
	v_fmamk_f32 v237, v93, 0x3dd53b94, v154
	v_fmamk_f32 v238, v94, 0x3dd53b94, v154
	v_fmamk_f32 v239, v95, 0x3dd53b94, v154
	v_fmamk_f32 v240, v96, 0x3dd53b94, v154
	v_fmamk_f32 v241, v97, 0x3dd53b94, v154
	s_waitcnt lgkmcnt(0)
	v_mfma_f32_32x32x16_bf16 v[82:97], v[66:69], v[142:145], 0
	v_fmamk_f32 v232, v79, 0x3dd53b94, v154
	v_fmamk_f32 v233, v80, 0x3dd53b94, v154
	v_fmamk_f32 v219, v74, 0x3dd53b94, v154
	v_fmamk_f32 v220, v75, 0x3dd53b94, v154
	v_fmamk_f32 v221, v76, 0x3dd53b94, v154
	v_fmamk_f32 v222, v77, 0x3dd53b94, v154
	v_fmamk_f32 v223, v78, 0x3dd53b94, v154
	v_fmac_f32_e32 v154, 0x3dd53b94, v81
	v_mfma_f32_32x32x16_bf16 v[66:81], v[70:73], v[142:145], 0
	v_exp_f32_e32 v224, v224
	v_exp_f32_e32 v225, v225
	v_exp_f32_e32 v226, v226
	v_mfma_f32_32x32x16_bf16 v[82:97], v[146:149], v[138:141], v[82:97]
	v_exp_f32_e32 v227, v227
	v_exp_f32_e32 v228, v228
	v_mfma_f32_32x32x16_bf16 v[66:81], v[150:153], v[138:141], v[66:81]
	ds_read_b128 v[146:149], v178 offset:32768
	ds_read_b128 v[150:153], v178 offset:40960
	v_exp_f32_e32 v229, v229
	v_exp_f32_e32 v230, v230
	s_cmp_lg_u32 s98, 0
	s_cbranch_scc1 .Lattn_mla_nopf
	s_add_u32 s0, s38, s20
	s_addc_u32 s1, s39, s21
	s_add_u32 s100, s0, s42
	s_addc_u32 s101, s1, s43
	s_mov_b32 m0, s93
	v_lshl_add_u64 v[254:255], v[246:247], 0, s[100:101]
	global_load_lds_dwordx4 v[254:255], off
	s_add_u32 s100, s0, s46
	s_addc_u32 s101, s1, s47
	s_mov_b32 m0, s94
	v_lshl_add_u64 v[254:255], v[246:247], 0, s[100:101]
	global_load_lds_dwordx4 v[254:255], off
	s_add_u32 s100, s0, s44
	s_addc_u32 s101, s1, s45
	s_add_i32 s98, s89, s24
	s_mov_b32 m0, s98
	v_lshl_add_u64 v[254:255], v[248:249], 0, s[100:101]
	global_load_lds_dwordx4 v[254:255], off
	s_add_u32 s100, s0, s50
	s_addc_u32 s101, s1, s51
	s_add_i32 m0, s98, 0x2000
	v_lshl_add_u64 v[254:255], v[248:249], 0, s[100:101]
	global_load_lds_dwordx4 v[254:255], off
	s_add_u32 s0, s38, s88
	s_addc_u32 s1, s39, s87
	s_add_u32 s0, s0, s58
	s_addc_u32 s1, s1, s59
	s_mov_b32 m0, s95
	v_lshl_add_u64 v[254:255], v[250:251], 0, s[0:1]
	global_load_lds_dwordx4 v[254:255], off
.Lattn_mla_nopf:
	s_waitcnt lgkmcnt(0)
	v_mfma_f32_32x32x16_bf16 v[82:97], v[146:149], v[134:137], v[82:97]
	v_mfma_f32_32x32x16_bf16 v[66:81], v[150:153], v[134:137], v[66:81]
	ds_read_b128 v[146:149], v180 offset:32768
	ds_read_b128 v[150:153], v180 offset:40960
	v_exp_f32_e32 v231, v231
	v_exp_f32_e32 v234, v234
	v_exp_f32_e32 v235, v235
	s_waitcnt lgkmcnt(0)
	v_mfma_f32_32x32x16_bf16 v[82:97], v[146:149], v[130:133], v[82:97]
	v_mfma_f32_32x32x16_bf16 v[66:81], v[150:153], v[130:133], v[66:81]
	ds_read_b128 v[146:149], v182 offset:32768
	ds_read_b128 v[150:153], v182 offset:40960
	v_exp_f32_e32 v236, v236
	v_exp_f32_e32 v237, v237
	v_exp_f32_e32 v238, v238
	s_waitcnt lgkmcnt(0)
	v_mfma_f32_32x32x16_bf16 v[82:97], v[146:149], v[126:129], v[82:97]
	v_mfma_f32_32x32x16_bf16 v[66:81], v[150:153], v[126:129], v[66:81]
	ds_read_b128 v[146:149], v186 offset:32768
	ds_read_b128 v[150:153], v186 offset:40960
	v_exp_f32_e32 v239, v239
	v_exp_f32_e32 v240, v240
	v_exp_f32_e32 v241, v241
	s_waitcnt lgkmcnt(0)
	v_mfma_f32_32x32x16_bf16 v[82:97], v[146:149], v[122:125], v[82:97]
	v_mfma_f32_32x32x16_bf16 v[66:81], v[150:153], v[122:125], v[66:81]
	ds_read_b128 v[146:149], v188 offset:32768
	ds_read_b128 v[150:153], v188 offset:40960
	v_exp_f32_e32 v155, v155
	v_exp_f32_e32 v156, v156
	v_exp_f32_e32 v157, v157
	s_waitcnt lgkmcnt(0)
	v_mfma_f32_32x32x16_bf16 v[82:97], v[146:149], v[118:121], v[82:97]
	v_mfma_f32_32x32x16_bf16 v[66:81], v[150:153], v[118:121], v[66:81]
	ds_read_b128 v[146:149], v190 offset:32768
	ds_read_b128 v[150:153], v190 offset:40960
	v_exp_f32_e32 v202, v202
	v_exp_f32_e32 v215, v215
	v_exp_f32_e32 v216, v216
	s_waitcnt lgkmcnt(0)
	v_mfma_f32_32x32x16_bf16 v[82:97], v[146:149], v[114:117], v[82:97]
	v_mfma_f32_32x32x16_bf16 v[66:81], v[150:153], v[114:117], v[66:81]
	ds_read_b128 v[146:149], v192
	ds_read_b128 v[150:153], v192 offset:4096
	v_exp_f32_e32 v217, v217
	v_exp_f32_e32 v218, v218
	v_exp_f32_e32 v219, v219
	s_waitcnt lgkmcnt(0)
	v_mfma_f32_32x32x16_bf16 v[82:97], v[146:149], v[110:113], v[82:97]
	v_mfma_f32_32x32x16_bf16 v[66:81], v[150:153], v[110:113], v[66:81]
	ds_read_b128 v[146:149], v194
	ds_read_b128 v[150:153], v194 offset:4096
	v_exp_f32_e32 v220, v220
	v_exp_f32_e32 v221, v221
	v_exp_f32_e32 v222, v222
	s_waitcnt lgkmcnt(0)
	v_mfma_f32_32x32x16_bf16 v[82:97], v[146:149], v[106:109], v[82:97]
	v_mfma_f32_32x32x16_bf16 v[66:81], v[150:153], v[106:109], v[66:81]
	ds_read_b128 v[146:149], v196
	ds_read_b128 v[150:153], v196 offset:4096
	v_exp_f32_e32 v223, v223
	v_exp_f32_e32 v242, v232
	v_exp_f32_e32 v243, v233
	s_waitcnt lgkmcnt(0)
	v_mfma_f32_32x32x16_bf16 v[82:97], v[146:149], v[102:105], v[82:97]
	v_mfma_f32_32x32x16_bf16 v[66:81], v[150:153], v[102:105], v[66:81]
	ds_read_b128 v[146:149], v199
	ds_read_b128 v[150:153], v199 offset:4096
	v_exp_f32_e32 v244, v154
	s_waitcnt lgkmcnt(0)
	v_mfma_f32_32x32x16_bf16 v[82:97], v[146:149], v[98:101], v[82:97]
	v_add_f32_e32 v146, 0, v224
	v_add_f32_e32 v146, v225, v146
	v_add_f32_e32 v146, v226, v146
	v_add_f32_e32 v146, v227, v146
	v_add_f32_e32 v146, v228, v146
	v_add_f32_e32 v146, v229, v146
	v_add_f32_e32 v146, v230, v146
	v_add_f32_e32 v146, v231, v146
	v_add_f32_e32 v146, v234, v146
	v_add_f32_e32 v146, v235, v146
	v_add_f32_e32 v146, v236, v146
	v_add_f32_e32 v146, v237, v146
	v_add_f32_e32 v146, v238, v146
	v_add_f32_e32 v146, v239, v146
	v_add_f32_e32 v146, v240, v146
	v_add_f32_e32 v146, v241, v146
	v_add_f32_e32 v146, v155, v146
	v_add_f32_e32 v146, v156, v146
	v_add_f32_e32 v146, v157, v146
	v_add_f32_e32 v146, v202, v146
	v_add_f32_e32 v146, v215, v146
	v_add_f32_e32 v146, v216, v146
	v_add_f32_e32 v146, v217, v146
	v_add_f32_e32 v146, v218, v146
	v_add_f32_e32 v146, v219, v146
	v_add_f32_e32 v146, v220, v146
	v_mfma_f32_32x32x16_bf16 v[66:81], v[150:153], v[98:101], v[66:81]
	v_add_f32_e32 v146, v221, v146
	v_add_f32_e32 v146, v222, v146
	v_add_f32_e32 v146, v223, v146
	v_add_f32_e32 v146, v242, v146
	v_add_f32_e32 v146, v243, v146
	v_add_f32_e32 v232, v244, v146
	v_mov_b32_e32 v233, v232
	s_nop 1
	v_permlane32_swap_b32_e32 v232, v233
	v_cvt_pk_bf16_f32 v146, v224, v225
	v_cvt_pk_bf16_f32 v147, v226, v227
	v_cvt_pk_bf16_f32 v148, v228, v229
	v_cvt_pk_bf16_f32 v149, v230, v231
	v_cvt_pk_bf16_f32 v150, v234, v235
	v_cvt_pk_bf16_f32 v151, v236, v237
	v_cvt_pk_bf16_f32 v152, v238, v239
	v_cvt_pk_bf16_f32 v153, v240, v241
	v_cvt_pk_bf16_f32 v154, v155, v156
	v_cvt_pk_bf16_f32 v155, v157, v202
	v_cvt_pk_bf16_f32 v156, v215, v216
	v_cvt_pk_bf16_f32 v157, v217, v218
	v_cvt_pk_bf16_f32 v216, v219, v220
	v_cvt_pk_bf16_f32 v217, v221, v222
	v_cvt_pk_bf16_f32 v218, v223, v242
	v_cvt_pk_bf16_f32 v219, v243, v244
	s_nop 0
	v_permlane32_swap_b32_e32 v146, v148
	v_permlane32_swap_b32_e32 v147, v149
	v_permlane32_swap_b32_e32 v150, v152
	v_permlane32_swap_b32_e32 v151, v153
	v_permlane32_swap_b32_e32 v154, v156
	v_permlane32_swap_b32_e32 v155, v157
	v_permlane32_swap_b32_e32 v216, v218
	v_permlane32_swap_b32_e32 v217, v219
	v_lshl_add_u32 v242, s23, 14, v200
	ds_read_b64_tr_b16 v[220:221], v242 offset:0
	ds_read_b64_tr_b16 v[222:223], v242 offset:0x800
	ds_read_b64_tr_b16 v[224:225], v242 offset:0x1000
	ds_read_b64_tr_b16 v[226:227], v242 offset:0x1800
	ds_read_b64_tr_b16 v[228:229], v242 offset:0x2000
	ds_read_b64_tr_b16 v[230:231], v242 offset:0x2800
	ds_read_b64_tr_b16 v[234:235], v242 offset:0x3000
	ds_read_b64_tr_b16 v[236:237], v242 offset:0x3800
	s_waitcnt lgkmcnt(0)
	s_nop 0
	v_mfma_f32_32x32x16_bf16 v[2:17], v[146:149], v[220:223], v[2:17]
	ds_read_b64_tr_b16 v[220:221], v242 offset:0x200
	ds_read_b64_tr_b16 v[222:223], v242 offset:0xa00
	v_max_f32_e32 v202, v83, v83
	v_max_f32_e32 v215, v82, v82
	v_max_f32_e32 v202, v215, v202
	v_max3_f32 v202, v202, v84, v85
	v_max3_f32 v202, v202, v86, v87
	v_mfma_f32_32x32x16_bf16 v[2:17], v[150:153], v[224:227], v[2:17]
	ds_read_b64_tr_b16 v[224:225], v242 offset:0x1200
	ds_read_b64_tr_b16 v[226:227], v242 offset:0x1a00
	v_max3_f32 v202, v202, v88, v89
	v_max3_f32 v202, v202, v90, v91
	v_max3_f32 v202, v202, v92, v93
	v_max3_f32 v202, v202, v94, v95
	v_max3_f32 v202, v202, v96, v97
	v_mfma_f32_32x32x16_bf16 v[2:17], v[154:157], v[228:231], v[2:17]
	ds_read_b64_tr_b16 v[228:229], v242 offset:0x2200
	ds_read_b64_tr_b16 v[230:231], v242 offset:0x2a00
	ds_read_b64_tr_b16 v[238:239], v242 offset:0x3200
	ds_read_b64_tr_b16 v[240:241], v242 offset:0x3a00
	s_waitcnt lgkmcnt(0)
	v_mfma_f32_32x32x16_bf16 v[2:17], v[216:219], v[234:237], v[2:17]
	v_mfma_f32_32x32x16_bf16 v[50:65], v[146:149], v[220:223], v[50:65]
	v_max3_f32 v202, v202, v66, v67
	v_max3_f32 v202, v202, v68, v69
	v_max3_f32 v202, v202, v70, v71
	v_max3_f32 v202, v202, v72, v73
	v_max3_f32 v202, v202, v74, v75
	v_max3_f32 v202, v202, v76, v77
	v_max3_f32 v202, v202, v78, v79
	v_mfma_f32_32x32x16_bf16 v[50:65], v[150:153], v[224:227], v[50:65]
	v_max3_f32 v202, v202, v80, v81
	v_mov_b32_e32 v215, v202
	s_nop 1
	v_permlane32_swap_b32_e32 v202, v215
	v_max_f32_e32 v215, v215, v215
	v_max_f32_e32 v202, v202, v202
	v_max_f32_e32 v202, v202, v215
	v_max_f32_e32 v220, v165, v165
	v_sub_f32_e32 v215, v202, v165
	v_max_f32_e32 v202, v220, v202
	v_sub_f32_e32 v220, v165, v202
	v_mul_f32_e32 v220, 0x3dd53b94, v220
	v_mfma_f32_32x32x16_bf16 v[50:65], v[154:157], v[228:231], v[50:65]
	v_exp_f32_e32 v220, v220
	v_cmp_ge_f32_e32 vcc, s77, v215
	s_cmp_eq_u64 vcc, exec
	s_cselect_b64 s[4:5], -1, 0
	v_cndmask_b32_e64 v215, v220, 1.0, s[4:5]
	ds_read_b64_tr_b16 v[220:221], v242 offset:0x400
	ds_read_b64_tr_b16 v[222:223], v242 offset:0xc00
	ds_read_b64_tr_b16 v[224:225], v242 offset:0x1400
	v_mfma_f32_32x32x16_bf16 v[50:65], v[216:219], v[238:241], v[50:65]
	ds_read_b64_tr_b16 v[226:227], v242 offset:0x1c00
	ds_read_b64_tr_b16 v[228:229], v242 offset:0x2400
	ds_read_b64_tr_b16 v[230:231], v242 offset:0x2c00
	ds_read_b64_tr_b16 v[234:235], v242 offset:0x3400
	ds_read_b64_tr_b16 v[236:237], v242 offset:0x3c00
	s_waitcnt lgkmcnt(0)
	v_mfma_f32_32x32x16_bf16 v[34:49], v[146:149], v[220:223], v[34:49]
	ds_read_b64_tr_b16 v[220:221], v242 offset:0x600
	ds_read_b64_tr_b16 v[222:223], v242 offset:0xe00
	v_mfma_f32_32x32x16_bf16 v[34:49], v[150:153], v[224:227], v[34:49]
	ds_read_b64_tr_b16 v[224:225], v242 offset:0x1600
	ds_read_b64_tr_b16 v[226:227], v242 offset:0x1e00
	v_mfma_f32_32x32x16_bf16 v[34:49], v[154:157], v[228:231], v[34:49]
	ds_read_b64_tr_b16 v[228:229], v242 offset:0x2600
	ds_read_b64_tr_b16 v[230:231], v242 offset:0x2e00
	ds_read_b64_tr_b16 v[238:239], v242 offset:0x3600
	ds_read_b64_tr_b16 v[240:241], v242 offset:0x3e00
	s_waitcnt lgkmcnt(0)
	v_mfma_f32_32x32x16_bf16 v[34:49], v[216:219], v[234:237], v[34:49]
	v_mfma_f32_32x32x16_bf16 v[18:33], v[146:149], v[220:223], v[18:33]
	v_cmp_gt_f32_e32 vcc, 1.0, v215
	v_mfma_f32_32x32x16_bf16 v[18:33], v[150:153], v[224:227], v[18:33]
	v_mfma_f32_32x32x16_bf16 v[18:33], v[154:157], v[228:231], v[18:33]
	v_mfma_f32_32x32x16_bf16 v[18:33], v[216:219], v[238:241], v[18:33]
	s_cbranch_vccz .LBB0_553
	s_and_saveexec_b64 s[0:1], s[2:3]
	ds_write_b32 v170, v215 offset:128
	s_or_b64 exec, exec, s[0:1]
	s_waitcnt lgkmcnt(0)
	ds_read_b128 v[146:149], v158 offset:224
	ds_read_b128 v[150:153], v158 offset:192
	ds_read_b128 v[154:157], v158 offset:160
	ds_read_b128 v[216:219], v158 offset:128
	s_waitcnt lgkmcnt(0)
	v_pk_mul_f32 v[16:17], v[16:17], v[148:149]
	v_pk_mul_f32 v[12:13], v[12:13], v[152:153]
	v_pk_mul_f32 v[8:9], v[8:9], v[156:157]
	v_pk_mul_f32 v[4:5], v[4:5], v[218:219]
	v_pk_mul_f32 v[14:15], v[14:15], v[146:147]
	v_pk_mul_f32 v[10:11], v[10:11], v[150:151]
	v_pk_mul_f32 v[6:7], v[6:7], v[154:155]
	v_pk_mul_f32 v[2:3], v[2:3], v[216:217]
	v_pk_mul_f32 v[64:65], v[64:65], v[148:149]
	v_pk_mul_f32 v[60:61], v[60:61], v[152:153]
	v_pk_mul_f32 v[56:57], v[56:57], v[156:157]
	v_pk_mul_f32 v[52:53], v[52:53], v[218:219]
	v_pk_mul_f32 v[62:63], v[62:63], v[146:147]
	v_pk_mul_f32 v[58:59], v[58:59], v[150:151]
	v_pk_mul_f32 v[54:55], v[54:55], v[154:155]
	v_pk_mul_f32 v[50:51], v[50:51], v[216:217]
	v_pk_mul_f32 v[48:49], v[48:49], v[148:149]
	v_pk_mul_f32 v[44:45], v[44:45], v[152:153]
	v_pk_mul_f32 v[40:41], v[40:41], v[156:157]
	v_pk_mul_f32 v[36:37], v[36:37], v[218:219]
	v_pk_mul_f32 v[46:47], v[46:47], v[146:147]
	v_pk_mul_f32 v[42:43], v[42:43], v[150:151]
	v_pk_mul_f32 v[38:39], v[38:39], v[154:155]
	v_pk_mul_f32 v[34:35], v[34:35], v[216:217]
	v_pk_mul_f32 v[32:33], v[32:33], v[148:149]
	v_pk_mul_f32 v[28:29], v[28:29], v[152:153]
	v_pk_mul_f32 v[24:25], v[24:25], v[156:157]
	v_pk_mul_f32 v[20:21], v[20:21], v[218:219]
	v_pk_mul_f32 v[30:31], v[30:31], v[146:147]
	v_pk_mul_f32 v[26:27], v[26:27], v[150:151]
	v_pk_mul_f32 v[22:23], v[22:23], v[154:155]
	v_pk_mul_f32 v[18:19], v[18:19], v[216:217]
